# f7 + mem-attention prologue: second Q pass loads issued with the first (register-renamed consumer block)
# baseline (speedup 1.0000x reference)
; #define LAS __attribute__((address_space(3)))
; __device__ __forceinline__ float bflo(unsigned u) { return __uint_as_float(u << 16); }
; __device__ __forceinline__ float bfhi(unsigned u) { return __uint_as_float(u & 0xffff0000u); }
; __device__ __forceinline__ float frsq(float x) { return __builtin_amdgcn_rsqf(x); }
; template <int DH, int NCOMP>
; __device__ __forceinline__ void tile_store_norm(const u32x4 (&r)[4], LAS unsigned char* buf, const LAS float* gain, float scale, int tid) {
;     constexpr int KST = DH * 2 + 16, CPR = DH / 8;
;     float ss[2] = {0.f, 0.f};
; #pragma unroll
;     for (int i = 0; i < 4; ++i) { const int c = (NCOMP == 2) ? (i >> 1) : 0;
;         const float a0 = bflo(r[i].x), a1 = bfhi(r[i].x), a2 = bflo(r[i].y), a3 = bfhi(r[i].y), a4 = bflo(r[i].z), a5 = bfhi(r[i].z), a6 = bflo(r[i].w), a7 = bfhi(r[i].w);
;         ss[c] += (a0 * a0 + a1 * a1) + (a2 * a2 + a3 * a3) + (a4 * a4 + a5 * a5) + (a6 * a6 + a7 * a7); }
; #pragma unroll
;     for (int c = 0; c < NCOMP; ++c) { ss[c] += __shfl_xor(ss[c], 1); ss[c] += __shfl_xor(ss[c], 2); ss[c] += __shfl_xor(ss[c], 4); ss[c] = frsq(ss[c] * (1.0f / DH) + NORM_EPS) * scale; }
;     template <bool BG = false>
;     __device__ __forceinline__ void run(LAS unsigned char* lds, f32x16 (&O)[NCOMP][NBLK], BgConv* bg = nullptr) const {
;     ...
; #pragma unroll
;         for (int pass = 0; pass < NRB / 2; ++pass) {
;             u32x4 qr[4]; tile_load(qr, Q + (size_t)(64 * pass) * ldq, ldq, tid);
;             tile_store_norm<DH, NCOMP>(qr, kbuf, gq, qscale, tid);
;             __syncthreads();
;             if (rbA / 2 == pass) {
; #pragma unroll
;                 for (int s = 0; s < KS; ++s) qf[s] = *(const LAS bf16x8*)(kbuf + ((32 * (rbA & 1) + r) * NCOMP + compA) * KST + (16 * s + 8 * h) * 2);
;             }
;             __syncthreads();
;         }
;         u32x4 kreg[4], vreg[4];
;         tile_load(kreg, K, ldk, tid); tile_load(vreg, V, ldv, tid);
.LBB0_671:
	s_or_b64 exec, exec, s[18:19]
	s_ashr_i32 s18, s33, 7
	s_lshl_b32 s19, s33, 7
	s_lshl_b32 s8, s18, 12
	s_and_b32 s19, s19, 0xf80
	s_or_b32 s36, s19, s8
	s_mul_i32 s19, s36, 0x3c00
	s_mul_hi_i32 s8, s36, 0x3c00
	s_add_u32 s19, s34, s19
	s_addc_u32 s21, s35, s8
	s_lshl_b32 s8, s33, 3
	s_and_b32 s8, s8, 0x300
	s_lshl_b32 s8, s8, 1
	s_add_u32 s19, s19, s8
	s_addc_u32 s21, s21, 0
	s_add_u32 s38, s19, 0x8003000
	v_ashrrev_i32_e32 v4, 3, v2
	v_lshlrev_b32_e32 v3, 3, v2
	s_addc_u32 s39, s21, 0
	v_and_b32_e32 v5, 56, v3
	v_mad_i64_i32 v[6:7], s[40:41], v4, s25, 0
	v_lshl_add_u64 v[6:7], v[6:7], 1, s[38:39]
	v_lshlrev_b32_e32 v162, 1, v5
	v_lshl_add_u64 v[6:7], v[6:7], 0, v[162:163]
	s_waitcnt lgkmcnt(0)
	s_barrier
	global_load_dwordx4 v[16:19], v[6:7], off offset:128
	global_load_dwordx4 v[20:23], v[6:7], off offset:256
	global_load_dwordx4 v[24:27], v[6:7], off
	global_load_dwordx4 v[30:33], v[6:7], off offset:384
	s_lshl_b32 s98, s18, 8
	s_ashr_i32 s99, s98, 31
	s_lshl_b64 s[98:99], s[98:99], 12
	s_add_u32 s98, s13, s98
	s_addc_u32 s99, s15, s99
	s_add_u32 s98, s98, s8
	s_addc_u32 s99, s99, 0
	v_mov_b32_e32 v228, v4
	v_ashrrev_i32_e32 v229, 31, v4
	v_lshlrev_b64 v[228:229], 12, v[228:229]
	v_lshl_add_u64 v[228:229], s[98:99], 0, v[228:229]
	v_lshl_add_u64 v[228:229], v[228:229], 0, v[162:163]
	global_load_dwordx4 v[212:215], v[228:229], off
	global_load_dwordx4 v[216:219], v[228:229], off offset:128
	global_load_dwordx4 v[220:223], v[228:229], off offset:256
	global_load_dwordx4 v[224:227], v[228:229], off offset:384
	v_lshl_add_u64 v[246:247], v[6:7], 0, s[16:17]
	v_add_co_u32_e32 v248, vcc, s26, v6
	s_nop 1
	v_addc_co_u32_e32 v249, vcc, 0, v7, vcc
	global_load_dwordx4 v[230:233], v[246:247], off offset:128
	global_load_dwordx4 v[234:237], v[246:247], off offset:256
	global_load_dwordx4 v[238:241], v[248:249], off
	global_load_dwordx4 v[242:245], v[246:247], off offset:384
	v_cmp_lt_i32_e32 vcc, v195, v196
	v_and_b32_e32 v64, 7, v2
	v_or_b32_e32 v10, 16, v64
	v_cndmask_b32_e32 v5, v194, v195, vcc
	v_cmp_lt_i32_e32 vcc, v197, v196
	v_lshlrev_b32_e32 v14, 2, v5
	v_mul_lo_u32 v5, v4, s23
	v_cndmask_b32_e32 v8, v194, v197, vcc
	v_cmp_lt_i32_e32 vcc, v198, v196
	v_lshlrev_b32_e32 v13, 2, v8
	v_lshlrev_b32_e32 v8, 5, v64
	v_cndmask_b32_e32 v9, v194, v198, vcc
	v_lshlrev_b32_e32 v12, 2, v9
	v_or_b32_e32 v9, 8, v64
	v_add_u32_e32 v29, 0, v5
	v_add_u32_e32 v15, s24, v8
	v_lshlrev_b32_e32 v5, 5, v9
	v_lshlrev_b32_e32 v8, 4, v9
	v_lshlrev_b32_e32 v34, 5, v10
	v_lshlrev_b32_e32 v35, 4, v10
	v_add_u32_e32 v10, s24, v5
	v_add_u32_e32 v9, v29, v8
	v_add_u32_e32 v8, s24, v34
	v_add_u32_e32 v5, v29, v35
	v_lshlrev_b32_e32 v28, 4, v64
	s_ashr_i32 s38, s20, 6
	s_lshr_b32 s19, s20, 31
	s_add_i32 s19, s38, s19
	s_ashr_i32 s37, s19, 1
	v_and_b32_e32 v200, 31, v2
	s_lshl_b32 s19, s37, 5
	v_add_u32_e32 v11, v29, v28
	v_bfe_u32 v201, v2, 5, 1
	v_lshlrev_b32_e32 v203, 4, v201
	s_add_i32 s21, s38, 3
	s_cmp_gt_u32 s21, 6
	s_waitcnt vmcnt(11)
	v_and_b32_e32 v37, 0xffff0000, v17
	v_and_b32_e32 v36, 0xffff0000, v16
	v_lshlrev_b32_e32 v35, 16, v17
	v_lshlrev_b32_e32 v34, 16, v16
	v_and_b32_e32 v41, 0xffff0000, v19
	v_and_b32_e32 v40, 0xffff0000, v18
	v_pk_mul_f32 v[16:17], v[36:37], v[36:37]
	v_lshlrev_b32_e32 v39, 16, v19
	v_lshlrev_b32_e32 v38, 16, v18
	v_pk_mul_f32 v[18:19], v[40:41], v[40:41]
	v_pk_fma_f32 v[16:17], v[34:35], v[34:35], v[16:17]
	v_pk_fma_f32 v[18:19], v[38:39], v[38:39], v[18:19]
	v_pk_add_f32 v[16:17], v[16:17], v[16:17] op_sel:[0,1] op_sel_hi:[1,0]
	s_waitcnt vmcnt(9)
	v_and_b32_e32 v49, 0xffff0000, v26
	v_and_b32_e32 v51, 0xffff0000, v24
	v_pk_add_f32 v[16:17], v[18:19], v[16:17]
	v_lshlrev_b32_e32 v46, 16, v27
	v_and_b32_e32 v47, 0xffff0000, v27
	v_lshlrev_b32_e32 v48, 16, v26
	v_and_b32_e32 v27, 0xffff0000, v25
	v_lshlrev_b32_e32 v50, 16, v24
	v_pk_add_f32 v[16:17], v[18:19], v[16:17] op_sel:[1,0] op_sel_hi:[0,1]
	v_mov_b32_e32 v18, v49
	v_mov_b32_e32 v19, v51
	v_lshlrev_b32_e32 v26, 16, v25
	v_mul_f32_e32 v54, v27, v27
	v_mov_b32_e32 v56, v48
	v_mov_b32_e32 v57, v50
	v_pk_mul_f32 v[18:19], v[18:19], v[18:19]
	v_pk_fma_f32 v[54:55], v[26:27], v[26:27], v[54:55] op_sel_hi:[1,1,0]
	v_pk_fma_f32 v[18:19], v[56:57], v[56:57], v[18:19]
	v_mul_f32_e32 v52, v47, v47
	v_pk_add_f32 v[54:55], v[18:19], v[54:55] op_sel:[1,0] op_sel_hi:[0,1]
	v_pk_fma_f32 v[52:53], v[46:47], v[46:47], v[52:53] op_sel_hi:[1,1,0]
	v_pk_add_f32 v[18:19], v[18:19], v[54:55]
	v_and_b32_e32 v43, 0xffff0000, v20
	v_and_b32_e32 v45, 0xffff0000, v21
	s_waitcnt vmcnt(8)
	v_pk_mov_b32 v[58:59], v[22:23], v[32:33] op_sel:[1,0]
	v_lshlrev_b32_e32 v61, 16, v32
	v_lshlrev_b32_e32 v32, 16, v33
	v_and_b32_e32 v33, 0xffff0000, v33
	v_pk_add_f32 v[18:19], v[52:53], v[18:19]
	v_lshlrev_b32_e32 v42, 16, v20
	v_lshlrev_b32_e32 v44, 16, v21
	v_mul_f32_e32 v20, v43, v43
	v_mul_f32_e32 v24, v45, v45
	v_lshlrev_b32_e32 v55, 16, v30
	v_and_b32_e32 v57, 0xffff0000, v30
	v_mul_f32_e32 v17, v33, v33
	v_mul_f32_e32 v19, v32, v32
	v_lshlrev_b32_e32 v30, 16, v31
	v_and_b32_e32 v31, 0xffff0000, v31
	v_pk_fma_f32 v[20:21], v[42:43], v[42:43], v[20:21] op_sel_hi:[1,1,0]
	v_pk_fma_f32 v[24:25], v[44:45], v[44:45], v[24:25] op_sel_hi:[1,1,0]
	v_and_b32_e32 v56, 0xffff0000, v22
	v_pk_add_f32 v[16:17], v[18:19], v[16:17]
	v_pk_mul_f32 v[18:19], v[30:31], v[30:31]
	v_lshlrev_b32_e32 v54, 16, v22
	v_lshlrev_b32_e32 v60, 16, v23
	v_and_b32_e32 v59, 0xffff0000, v59
	v_and_b32_e32 v58, 0xffff0000, v58
	v_pk_mul_f32 v[22:23], v[56:57], v[56:57]
	v_mov_b32_e32 v21, v18
	v_mov_b32_e32 v25, v19
	v_pk_fma_f32 v[22:23], v[54:55], v[54:55], v[22:23]
	v_pk_mul_f32 v[62:63], v[58:59], v[58:59]
	v_pk_add_f32 v[18:19], v[20:21], v[24:25]
	v_pk_fma_f32 v[62:63], v[60:61], v[60:61], v[62:63]
	v_pk_add_f32 v[18:19], v[22:23], v[18:19]
	v_mov_b32_e32 v52, v34
	v_pk_add_f32 v[18:19], v[62:63], v[18:19]
	v_mov_b32_e32 v53, v36
	v_pk_add_f32 v[16:17], v[16:17], v[18:19]
	v_or_b32_e32 v19, 24, v64
	v_add_f32_e32 v16, v16, v17
	ds_bpermute_b32 v18, v14, v16
	v_lshlrev_b32_e32 v17, 5, v19
	v_lshlrev_b32_e32 v19, 4, v19
	v_mov_b32_e32 v36, v35
	v_mov_b32_e32 v35, v40
	s_waitcnt lgkmcnt(0)
; #define LAS __attribute__((address_space(3)))
; __device__ __forceinline__ unsigned pk2(float lo, float hi) { f32x2 v = {lo, hi}; bf16x2_t b = __builtin_convertvector(v, bf16x2_t); return __builtin_bit_cast(unsigned, b); }
; __device__ __forceinline__ float bflo(unsigned u) { return __uint_as_float(u << 16); }
; template <int DH, int NCOMP>
; __device__ __forceinline__ void tile_store_norm(const u32x4 (&r)[4], LAS unsigned char* buf, const LAS float* gain, float scale, int tid) {
;     ...
;     for (int i = 0; i < 4; ++i) { const int c = (NCOMP == 2) ? (i >> 1) : 0;
;         const float a0 = bflo(r[i].x), a1 = bfhi(r[i].x), a2 = bflo(r[i].y), a3 = bfhi(r[i].y), a4 = bflo(r[i].z), a5 = bfhi(r[i].z), a6 = bflo(r[i].w), a7 = bfhi(r[i].w);
;         ss[c] += (a0 * a0 + a1 * a1) + (a2 * a2 + a3 * a3) + (a4 * a4 + a5 * a5) + (a6 * a6 + a7 * a7); }
; #pragma unroll
;     for (int c = 0; c < NCOMP; ++c) { ss[c] += __shfl_xor(ss[c], 1); ss[c] += __shfl_xor(ss[c], 2); ss[c] += __shfl_xor(ss[c], 4); ss[c] = frsq(ss[c] * (1.0f / DH) + NORM_EPS) * scale; }
; #pragma unroll
;     for (int i = 0; i < 4; ++i) { const int c = (NCOMP == 2) ? (i >> 1) : 0; const int chunk = (tid & 7) + 8 * i, dch = chunk % CPR; const float rn = ss[c];
;         const f32x4 g0 = *(const LAS f32x4*)(gain + dch * 8), g1 = *(const LAS f32x4*)(gain + dch * 8 + 4);
;         u32x4 w;
;         w.x = pk2(bflo(r[i].x) * rn * g0[0], bfhi(r[i].x) * rn * g0[1]); w.y = pk2(bflo(r[i].y) * rn * g0[2], bfhi(r[i].y) * rn * g0[3]);
;         w.z = pk2(bflo(r[i].z) * rn * g1[0], bfhi(r[i].z) * rn * g1[1]); w.w = pk2(bflo(r[i].w) * rn * g1[2], bfhi(r[i].w) * rn * g1[3]);
;         *(LAS u32x4*)(buf + ((tid >> 3) * NCOMP + c) * KST + dch * 16) = w; }
; }
;     template <bool BG = false>
;     __device__ __forceinline__ void run(LAS unsigned char* lds, f32x16 (&O)[NCOMP][NBLK], BgConv* bg = nullptr) const {
;     ...
; #pragma unroll
;         for (int pass = 0; pass < NRB / 2; ++pass) {
;             u32x4 qr[4]; tile_load(qr, Q + (size_t)(64 * pass) * ldq, ldq, tid);
;             tile_store_norm<DH, NCOMP>(qr, kbuf, gq, qscale, tid);
;             __syncthreads();
;             if (rbA / 2 == pass) {
; #pragma unroll
;                 for (int s = 0; s < KS; ++s) qf[s] = *(const LAS bf16x8*)(kbuf + ((32 * (rbA & 1) + r) * NCOMP + compA) * KST + (16 * s + 8 * h) * 2);
;             }
;             __syncthreads();
;         }
	v_add_f32_e32 v18, v16, v18
	ds_bpermute_b32 v20, v13, v18
	v_add_u32_e32 v16, v29, v19
	v_and_or_b32 v19, s19, 32, v200
	v_mad_u32_u24 v62, v19, s23, 0
	v_mov_b32_e32 v40, v39
	s_waitcnt lgkmcnt(0)
	v_add_f32_e32 v63, v18, v20
	ds_bpermute_b32 v64, v12, v63
	ds_read_b128 v[18:21], v15
	ds_read_b128 v[22:25], v15 offset:16
	v_add_u32_e32 v17, s24, v17
	s_waitcnt lgkmcnt(2)
	v_add_f32_e32 v34, v63, v64
	v_fmamk_f32 v34, v34, 0x3b800000, v199
	v_rsq_f32_e32 v63, v34
	v_mov_b32_e32 v34, v38
	v_mul_f32_e32 v38, 0x3db8aa3b, v63
	v_pk_mul_f32 v[50:51], v[38:39], v[50:51] op_sel_hi:[0,1]
	v_pk_mul_f32 v[26:27], v[38:39], v[26:27] op_sel_hi:[0,1]
	s_waitcnt lgkmcnt(1)
	v_pk_mul_f32 v[18:19], v[18:19], v[50:51]
	v_pk_mul_f32 v[20:21], v[20:21], v[26:27]
	v_cvt_pk_bf16_f32 v18, v18, v19
	v_cvt_pk_bf16_f32 v19, v20, v21
	v_pk_mul_f32 v[20:21], v[38:39], v[48:49] op_sel_hi:[0,1]
	s_waitcnt lgkmcnt(0)
	v_pk_mul_f32 v[20:21], v[22:23], v[20:21]
	v_pk_mul_f32 v[22:23], v[38:39], v[46:47] op_sel_hi:[0,1]
	v_pk_mul_f32 v[22:23], v[24:25], v[22:23]
	v_cvt_pk_bf16_f32 v20, v20, v21
	v_cvt_pk_bf16_f32 v21, v22, v23
	ds_write_b128 v11, v[18:21]
	ds_read_b128 v[18:21], v10
	ds_read_b128 v[22:25], v10 offset:16
	v_pk_mul_f32 v[46:47], v[38:39], v[52:53] op_sel_hi:[0,1]
	v_pk_mul_f32 v[36:37], v[38:39], v[36:37] op_sel_hi:[0,1]
	v_mov_b32_e32 v26, v54
	s_waitcnt lgkmcnt(1)
	v_pk_mul_f32 v[18:19], v[18:19], v[46:47]
	v_pk_mul_f32 v[20:21], v[20:21], v[36:37]
	v_cvt_pk_bf16_f32 v18, v18, v19
	v_cvt_pk_bf16_f32 v19, v20, v21
	v_pk_mul_f32 v[20:21], v[38:39], v[34:35] op_sel_hi:[0,1]
	s_waitcnt lgkmcnt(0)
	v_pk_mul_f32 v[20:21], v[22:23], v[20:21]
	v_pk_mul_f32 v[22:23], v[38:39], v[40:41] op_sel_hi:[0,1]
	v_pk_mul_f32 v[22:23], v[24:25], v[22:23]
	v_cvt_pk_bf16_f32 v20, v20, v21
	v_cvt_pk_bf16_f32 v21, v22, v23
	ds_write_b128 v9, v[18:21]
	ds_read_b128 v[18:21], v8
	ds_read_b128 v[22:25], v8 offset:16
	v_pk_mul_f32 v[36:37], v[38:39], v[42:43] op_sel_hi:[0,1]
	v_mov_b32_e32 v27, v56
	v_mov_b32_e32 v34, v60
	s_waitcnt lgkmcnt(1)
	v_pk_mul_f32 v[18:19], v[18:19], v[36:37]
	v_pk_mul_f32 v[36:37], v[38:39], v[44:45] op_sel_hi:[0,1]
	v_pk_mul_f32 v[20:21], v[20:21], v[36:37]
	v_mov_b32_e32 v35, v58
	v_cvt_pk_bf16_f32 v18, v18, v19
	v_cvt_pk_bf16_f32 v19, v20, v21
	v_pk_mul_f32 v[20:21], v[38:39], v[26:27] op_sel_hi:[0,1]
	s_waitcnt lgkmcnt(0)
	v_pk_mul_f32 v[20:21], v[22:23], v[20:21]
	v_pk_mul_f32 v[22:23], v[38:39], v[34:35] op_sel_hi:[0,1]
	v_pk_mul_f32 v[22:23], v[24:25], v[22:23]
	v_cvt_pk_bf16_f32 v20, v20, v21
	v_cvt_pk_bf16_f32 v21, v22, v23
	ds_write_b128 v5, v[18:21]
	ds_read_b128 v[18:21], v17
	ds_read_b128 v[22:25], v17 offset:16
	v_mov_b32_e32 v56, v55
	v_pk_mul_f32 v[26:27], v[38:39], v[56:57] op_sel_hi:[0,1]
	v_mov_b32_e32 v58, v61
	s_waitcnt lgkmcnt(1)
	v_pk_mul_f32 v[18:19], v[18:19], v[26:27]
	v_pk_mul_f32 v[26:27], v[38:39], v[30:31] op_sel_hi:[0,1]
	v_pk_mul_f32 v[20:21], v[20:21], v[26:27]
	v_cvt_pk_bf16_f32 v18, v18, v19
	v_cvt_pk_bf16_f32 v19, v20, v21
	v_pk_mul_f32 v[20:21], v[38:39], v[58:59] op_sel_hi:[0,1]
	s_waitcnt lgkmcnt(0)
	v_pk_mul_f32 v[20:21], v[22:23], v[20:21]
	v_pk_mul_f32 v[22:23], v[38:39], v[32:33] op_sel_hi:[0,1]
	v_pk_mul_f32 v[22:23], v[24:25], v[22:23]
	v_cvt_pk_bf16_f32 v20, v20, v21
	v_cvt_pk_bf16_f32 v21, v22, v23
	ds_write_b128 v16, v[18:21]
	v_add_u32_e32 v18, v62, v203
	s_waitcnt lgkmcnt(0)
	s_barrier
	s_cbranch_scc1 .LBB0_673
	ds_read_b128 v[142:145], v18
	ds_read_b128 v[138:141], v18 offset:32
	ds_read_b128 v[134:137], v18 offset:64
	ds_read_b128 v[130:133], v18 offset:96
	ds_read_b128 v[126:129], v18 offset:128
	ds_read_b128 v[122:125], v18 offset:160
	ds_read_b128 v[118:121], v18 offset:192
	ds_read_b128 v[114:117], v18 offset:224
	ds_read_b128 v[110:113], v18 offset:256
	ds_read_b128 v[106:109], v18 offset:288
	ds_read_b128 v[102:105], v18 offset:320
	ds_read_b128 v[98:101], v18 offset:352
	ds_read_b128 v[94:97], v18 offset:384
	ds_read_b128 v[90:93], v18 offset:416
	ds_read_b128 v[86:89], v18 offset:448
	ds_read_b128 v[82:85], v18 offset:480
.LBB0_673:
	v_lshl_add_u64 v[34:35], v[6:7], 0, s[16:17]
	v_add_co_u32_e32 v6, vcc, s26, v6
	s_waitcnt lgkmcnt(0)
	s_nop 0
	v_addc_co_u32_e32 v7, vcc, 0, v7, vcc
	s_barrier
	s_and_b32 s20, s20, 0xffffff00
	s_cmpk_lg_i32 s20, 0x100
	s_waitcnt vmcnt(3)
	v_and_b32_e32 v39, 0xffff0000, v231
	v_and_b32_e32 v38, 0xffff0000, v230
	s_waitcnt vmcnt(1)
	v_and_b32_e32 v51, 0xffff0000, v240
	v_and_b32_e32 v53, 0xffff0000, v238
	v_lshlrev_b32_e32 v7, 16, v231
	v_lshlrev_b32_e32 v6, 16, v230
	v_lshlrev_b32_e32 v41, 16, v233
	v_lshlrev_b32_e32 v40, 16, v232
	v_and_b32_e32 v43, 0xffff0000, v233
	v_and_b32_e32 v42, 0xffff0000, v232
	v_lshlrev_b32_e32 v48, 16, v241
	v_and_b32_e32 v49, 0xffff0000, v241
	v_lshlrev_b32_e32 v50, 16, v240
	v_and_b32_e32 v241, 0xffff0000, v239
	v_lshlrev_b32_e32 v52, 16, v238
	v_pk_mul_f32 v[232:233], v[38:39], v[38:39]
	v_mov_b32_e32 v66, v51
	v_mov_b32_e32 v67, v53
	v_lshlrev_b32_e32 v44, 16, v234
	v_and_b32_e32 v45, 0xffff0000, v234
	v_lshlrev_b32_e32 v46, 16, v235
	v_and_b32_e32 v47, 0xffff0000, v235
	v_lshlrev_b32_e32 v240, 16, v239
	v_pk_mul_f32 v[234:235], v[42:43], v[42:43]
	v_mul_f32_e32 v62, v241, v241
	v_mov_b32_e32 v64, v50
	v_mov_b32_e32 v65, v52
	v_pk_fma_f32 v[232:233], v[6:7], v[6:7], v[232:233]
	v_pk_mul_f32 v[66:67], v[66:67], v[66:67]
	s_waitcnt vmcnt(0)
; #define LAS __attribute__((address_space(3)))
; __device__ __forceinline__ unsigned pk2(float lo, float hi) { f32x2 v = {lo, hi}; bf16x2_t b = __builtin_convertvector(v, bf16x2_t); return __builtin_bit_cast(unsigned, b); }
; __device__ __forceinline__ float bflo(unsigned u) { return __uint_as_float(u << 16); }
; __device__ __forceinline__ float bfhi(unsigned u) { return __uint_as_float(u & 0xffff0000u); }
; __device__ __forceinline__ float frsq(float x) { return __builtin_amdgcn_rsqf(x); }
; template <int DH, int NCOMP>
; __device__ __forceinline__ void tile_store_norm(const u32x4 (&r)[4], LAS unsigned char* buf, const LAS float* gain, float scale, int tid) {
;     constexpr int KST = DH * 2 + 16, CPR = DH / 8;
;     float ss[2] = {0.f, 0.f};
; #pragma unroll
;     for (int i = 0; i < 4; ++i) { const int c = (NCOMP == 2) ? (i >> 1) : 0;
;         const float a0 = bflo(r[i].x), a1 = bfhi(r[i].x), a2 = bflo(r[i].y), a3 = bfhi(r[i].y), a4 = bflo(r[i].z), a5 = bfhi(r[i].z), a6 = bflo(r[i].w), a7 = bfhi(r[i].w);
;         ss[c] += (a0 * a0 + a1 * a1) + (a2 * a2 + a3 * a3) + (a4 * a4 + a5 * a5) + (a6 * a6 + a7 * a7); }
; #pragma unroll
;     for (int c = 0; c < NCOMP; ++c) { ss[c] += __shfl_xor(ss[c], 1); ss[c] += __shfl_xor(ss[c], 2); ss[c] += __shfl_xor(ss[c], 4); ss[c] = frsq(ss[c] * (1.0f / DH) + NORM_EPS) * scale; }
; #pragma unroll
;     for (int i = 0; i < 4; ++i) { const int c = (NCOMP == 2) ? (i >> 1) : 0; const int chunk = (tid & 7) + 8 * i, dch = chunk % CPR; const float rn = ss[c];
;         const f32x4 g0 = *(const LAS f32x4*)(gain + dch * 8), g1 = *(const LAS f32x4*)(gain + dch * 8 + 4);
;         u32x4 w;
;         w.x = pk2(bflo(r[i].x) * rn * g0[0], bfhi(r[i].x) * rn * g0[1]); w.y = pk2(bflo(r[i].y) * rn * g0[2], bfhi(r[i].y) * rn * g0[3]);
;         w.z = pk2(bflo(r[i].z) * rn * g1[0], bfhi(r[i].z) * rn * g1[1]); w.w = pk2(bflo(r[i].w) * rn * g1[2], bfhi(r[i].w) * rn * g1[3]);
;         *(LAS u32x4*)(buf + ((tid >> 3) * NCOMP + c) * KST + dch * 16) = w; }
; }
;     template <bool BG = false>
;     __device__ __forceinline__ void run(LAS unsigned char* lds, f32x16 (&O)[NCOMP][NBLK], BgConv* bg = nullptr) const {
;     ...
;             if (rbA / 2 == pass) {
; #pragma unroll
;                 for (int s = 0; s < KS; ++s) qf[s] = *(const LAS bf16x8*)(kbuf + ((32 * (rbA & 1) + r) * NCOMP + compA) * KST + (16 * s + 8 * h) * 2);
;             }
	v_lshlrev_b32_e32 v239, 16, v242
	v_lshlrev_b32_e32 v238, 16, v236
	v_and_b32_e32 v55, 0xffff0000, v242
	v_and_b32_e32 v54, 0xffff0000, v236
	v_pk_mov_b32 v[230:231], v[236:237], v[244:245] op_sel:[1,0]
	v_lshlrev_b32_e32 v242, 16, v243
	v_and_b32_e32 v243, 0xffff0000, v243
	v_mul_f32_e32 v236, v45, v45
	v_mul_f32_e32 v58, v47, v47
	v_pk_fma_f32 v[234:235], v[40:41], v[40:41], v[234:235]
	v_pk_fma_f32 v[62:63], v[240:241], v[240:241], v[62:63] op_sel_hi:[1,1,0]
	v_pk_add_f32 v[232:233], v[232:233], v[232:233] op_sel:[0,1] op_sel_hi:[1,0]
	v_pk_fma_f32 v[64:65], v[64:65], v[64:65], v[66:67]
	v_lshlrev_b32_e32 v56, 16, v237
	v_mul_f32_e32 v60, v49, v49
	v_pk_mul_f32 v[70:71], v[242:243], v[242:243]
	v_pk_fma_f32 v[236:237], v[44:45], v[44:45], v[236:237] op_sel_hi:[1,1,0]
	v_pk_fma_f32 v[58:59], v[46:47], v[46:47], v[58:59] op_sel_hi:[1,1,0]
	v_pk_add_f32 v[232:233], v[234:235], v[232:233]
	v_pk_add_f32 v[62:63], v[64:65], v[62:63] op_sel:[1,0] op_sel_hi:[0,1]
	v_and_b32_e32 v69, 0xffff0000, v231
	v_and_b32_e32 v68, 0xffff0000, v230
	v_pk_mul_f32 v[230:231], v[54:55], v[54:55]
	v_pk_fma_f32 v[60:61], v[48:49], v[48:49], v[60:61] op_sel_hi:[1,1,0]
	v_mov_b32_e32 v237, v70
	v_mov_b32_e32 v59, v71
	v_pk_add_f32 v[232:233], v[234:235], v[232:233] op_sel:[1,0] op_sel_hi:[0,1]
	v_pk_add_f32 v[234:235], v[64:65], v[62:63]
	v_lshlrev_b32_e32 v57, 16, v244
	v_lshlrev_b32_e32 v244, 16, v245
	v_and_b32_e32 v245, 0xffff0000, v245
	v_pk_fma_f32 v[230:231], v[238:239], v[238:239], v[230:231]
	v_pk_mul_f32 v[72:73], v[68:69], v[68:69]
	v_pk_add_f32 v[236:237], v[236:237], v[58:59]
	v_pk_add_f32 v[234:235], v[60:61], v[234:235]
	v_pk_fma_f32 v[66:67], v[56:57], v[56:57], v[72:73]
	v_pk_add_f32 v[230:231], v[230:231], v[236:237]
	v_mul_f32_e32 v233, v245, v245
	v_mul_f32_e32 v235, v244, v244
	v_pk_add_f32 v[230:231], v[66:67], v[230:231]
	v_pk_add_f32 v[232:233], v[234:235], v[232:233]
	v_mov_b32_e32 v58, v6
	v_pk_add_f32 v[230:231], v[232:233], v[230:231]
	v_mov_b32_e32 v6, v40
	v_add_f32_e32 v19, v230, v231
	ds_bpermute_b32 v14, v14, v19
	ds_read_b128 v[230:233], v15
	ds_read_b128 v[234:237], v15 offset:16
	v_mov_b32_e32 v40, v238
	v_mov_b32_e32 v59, v38
	v_mov_b32_e32 v38, v7
	s_waitcnt lgkmcnt(2)
	v_add_f32_e32 v14, v19, v14
	ds_bpermute_b32 v13, v13, v14
	v_mov_b32_e32 v7, v42
	v_mov_b32_e32 v42, v41
	v_mov_b32_e32 v41, v54
	v_mov_b32_e32 v54, v239
	s_waitcnt lgkmcnt(0)
	v_add_f32_e32 v13, v14, v13
	ds_bpermute_b32 v12, v12, v13
	s_waitcnt lgkmcnt(0)
	v_add_f32_e32 v12, v13, v12
	v_fmamk_f32 v12, v12, 0x3b800000, v199
	v_rsq_f32_e32 v12, v12
	s_nop 0
	v_mul_f32_e32 v238, 0x3db8aa3b, v12
	v_pk_mul_f32 v[12:13], v[238:239], v[52:53] op_sel_hi:[0,1]
	v_pk_mul_f32 v[14:15], v[238:239], v[240:241] op_sel_hi:[0,1]
	v_pk_mul_f32 v[240:241], v[238:239], v[50:51] op_sel_hi:[0,1]
	v_pk_mul_f32 v[48:49], v[238:239], v[48:49] op_sel_hi:[0,1]
	v_pk_mul_f32 v[12:13], v[230:231], v[12:13]
	v_pk_mul_f32 v[14:15], v[232:233], v[14:15]
	v_pk_mul_f32 v[230:231], v[234:235], v[240:241]
	v_pk_mul_f32 v[232:233], v[236:237], v[48:49]
	v_cvt_pk_bf16_f32 v12, v12, v13
	v_cvt_pk_bf16_f32 v13, v14, v15
	v_cvt_pk_bf16_f32 v14, v230, v231
	v_cvt_pk_bf16_f32 v15, v232, v233
	ds_write_b128 v11, v[12:15]
	ds_read_b128 v[12:15], v10
	ds_read_b128 v[230:233], v10 offset:16
	v_pk_mul_f32 v[234:235], v[238:239], v[58:59] op_sel_hi:[0,1]
	v_pk_mul_f32 v[6:7], v[238:239], v[6:7] op_sel_hi:[0,1]
	v_pk_mul_f32 v[10:11], v[238:239], v[38:39] op_sel_hi:[0,1]
	s_waitcnt lgkmcnt(1)
	v_pk_mul_f32 v[12:13], v[12:13], v[234:235]
	s_waitcnt lgkmcnt(0)
	v_pk_mul_f32 v[6:7], v[230:231], v[6:7]
	v_pk_mul_f32 v[14:15], v[14:15], v[10:11]
	v_cvt_pk_bf16_f32 v10, v12, v13
	v_cvt_pk_bf16_f32 v12, v6, v7
	v_pk_mul_f32 v[6:7], v[238:239], v[42:43] op_sel_hi:[0,1]
	v_pk_mul_f32 v[6:7], v[232:233], v[6:7]
	v_cvt_pk_bf16_f32 v11, v14, v15
	v_cvt_pk_bf16_f32 v13, v6, v7
	ds_write_b128 v9, v[10:13]
	ds_read_b128 v[10:13], v8
	ds_read_b128 v[6:9], v8 offset:16
	v_pk_mul_f32 v[230:231], v[238:239], v[44:45] op_sel_hi:[0,1]
	v_mov_b32_e32 v14, v56
	v_mov_b32_e32 v15, v68
	s_waitcnt lgkmcnt(1)
	v_pk_mul_f32 v[10:11], v[10:11], v[230:231]
	v_pk_mul_f32 v[230:231], v[238:239], v[46:47] op_sel_hi:[0,1]
	v_pk_mul_f32 v[12:13], v[12:13], v[230:231]
	v_cvt_pk_bf16_f32 v10, v10, v11
	v_cvt_pk_bf16_f32 v11, v12, v13
	v_pk_mul_f32 v[12:13], v[238:239], v[40:41] op_sel_hi:[0,1]
	s_waitcnt lgkmcnt(0)
	v_pk_mul_f32 v[6:7], v[6:7], v[12:13]
	v_mov_b32_e32 v68, v57
	v_cvt_pk_bf16_f32 v12, v6, v7
	v_pk_mul_f32 v[6:7], v[238:239], v[14:15] op_sel_hi:[0,1]
	v_pk_mul_f32 v[6:7], v[8:9], v[6:7]
	v_pk_mul_f32 v[14:15], v[238:239], v[54:55] op_sel_hi:[0,1]
	v_cvt_pk_bf16_f32 v13, v6, v7
	ds_write_b128 v5, v[10:13]
	ds_read_b128 v[6:9], v17
	ds_read_b128 v[10:13], v17 offset:16
	s_waitcnt lgkmcnt(1)
	v_pk_mul_f32 v[6:7], v[6:7], v[14:15]
	v_pk_mul_f32 v[14:15], v[238:239], v[242:243] op_sel_hi:[0,1]
	v_pk_mul_f32 v[8:9], v[8:9], v[14:15]
	v_cvt_pk_bf16_f32 v6, v6, v7
	v_cvt_pk_bf16_f32 v7, v8, v9
	v_pk_mul_f32 v[8:9], v[238:239], v[68:69] op_sel_hi:[0,1]
	s_waitcnt lgkmcnt(0)
	v_pk_mul_f32 v[8:9], v[10:11], v[8:9]
	v_pk_mul_f32 v[10:11], v[238:239], v[244:245] op_sel_hi:[0,1]
	v_pk_mul_f32 v[10:11], v[12:13], v[10:11]
	v_cvt_pk_bf16_f32 v8, v8, v9
	v_cvt_pk_bf16_f32 v9, v10, v11
	ds_write_b128 v16, v[6:9]
	s_waitcnt lgkmcnt(0)
	s_barrier
	s_cbranch_scc1 .LBB0_675
	ds_read_b128 v[142:145], v18
	ds_read_b128 v[138:141], v18 offset:32
	ds_read_b128 v[134:137], v18 offset:64
	ds_read_b128 v[130:133], v18 offset:96
	ds_read_b128 v[126:129], v18 offset:128
	ds_read_b128 v[122:125], v18 offset:160
	ds_read_b128 v[118:121], v18 offset:192
	ds_read_b128 v[114:117], v18 offset:224
	ds_read_b128 v[110:113], v18 offset:256
	ds_read_b128 v[106:109], v18 offset:288
	ds_read_b128 v[102:105], v18 offset:320
	ds_read_b128 v[98:101], v18 offset:352
	ds_read_b128 v[94:97], v18 offset:384
	ds_read_b128 v[90:93], v18 offset:416
	ds_read_b128 v[86:89], v18 offset:448
	ds_read_b128 v[82:85], v18 offset:480
